# attention phase: row-sum adds re-encoded e64 to e32 (same arithmetic) on top of v31
# baseline (speedup 1.0000x reference)
.LBB0_319:
	s_and_b64 vcc, exec, s[80:81]
	v_add_u32_e32 v199, s88, v195
	s_cbranch_vccz .LBB0_321
	ds_read_b64_tr_b16 v[146:147], v199 offset:0
	ds_read_b64_tr_b16 v[148:149], v199 offset:0x200
	ds_read_b64_tr_b16 v[150:151], v199 offset:0x400
	ds_read_b64_tr_b16 v[152:153], v199 offset:0x600
	ds_read_b64_tr_b16 v[154:155], v199 offset:0x800
	ds_read_b64_tr_b16 v[156:157], v199 offset:0xa00
	ds_read_b64_tr_b16 v[158:159], v199 offset:0xc00
	ds_read_b64_tr_b16 v[160:161], v199 offset:0xe00
	ds_read_b64_tr_b16 v[162:163], v199 offset:0x1000
	ds_read_b64_tr_b16 v[164:165], v199 offset:0x1200
	ds_read_b64_tr_b16 v[166:167], v199 offset:0x1400
	ds_read_b64_tr_b16 v[168:169], v199 offset:0x1600
	ds_read_b64_tr_b16 v[200:201], v199 offset:0x1800
	ds_read_b64_tr_b16 v[202:203], v199 offset:0x1a00
	ds_read_b64_tr_b16 v[204:205], v199 offset:0x1c00
	ds_read_b64_tr_b16 v[206:207], v199 offset:0x1e00
	v_exp_f32_e32 v98, v98
	v_exp_f32_e32 v99, v99
	v_exp_f32_e32 v100, v100
	v_exp_f32_e32 v101, v101
	v_exp_f32_e32 v102, v102
	v_exp_f32_e32 v103, v103
	v_exp_f32_e32 v104, v104
	v_exp_f32_e32 v105, v105
	v_exp_f32_e32 v106, v106
	v_exp_f32_e32 v107, v107
	v_exp_f32_e32 v108, v108
	v_exp_f32_e32 v109, v109
	v_exp_f32_e32 v110, v110
	v_exp_f32_e32 v111, v111
	v_exp_f32_e32 v112, v112
	v_exp_f32_e32 v113, v113
	v_cvt_pk_bf16_f32 v208, v98, v99
	v_cvt_pk_bf16_f32 v209, v100, v101
	v_cvt_pk_bf16_f32 v210, v102, v103
	v_cvt_pk_bf16_f32 v211, v104, v105
	v_cvt_pk_bf16_f32 v212, v106, v107
	v_cvt_pk_bf16_f32 v213, v108, v109
	v_cvt_pk_bf16_f32 v214, v110, v111
	v_cvt_pk_bf16_f32 v215, v112, v113
	s_waitcnt lgkmcnt(0)
	s_nop 0
	v_mfma_f32_32x32x16_bf16 v[50:65], v[146:149], v[208:211], v[50:65]
	v_exp_f32_e32 v82, v82
	v_exp_f32_e32 v83, v83
	v_exp_f32_e32 v84, v84
	v_exp_f32_e32 v85, v85
	v_mfma_f32_32x32x16_bf16 v[18:33], v[162:165], v[208:211], v[18:33]
	v_exp_f32_e32 v86, v86
	v_exp_f32_e32 v87, v87
	v_exp_f32_e32 v88, v88
	v_exp_f32_e32 v89, v89
	v_mfma_f32_32x32x16_bf16 v[50:65], v[150:153], v[212:215], v[50:65]
	v_exp_f32_e32 v90, v90
	v_exp_f32_e32 v91, v91
	v_exp_f32_e32 v92, v92
	v_exp_f32_e32 v93, v93
	v_mfma_f32_32x32x16_bf16 v[18:33], v[166:169], v[212:215], v[18:33]
	v_exp_f32_e32 v94, v94
	v_exp_f32_e32 v95, v95
	v_exp_f32_e32 v96, v96
	v_exp_f32_e32 v97, v97
	v_cvt_pk_bf16_f32 v146, v82, v83
	v_cvt_pk_bf16_f32 v147, v84, v85
	v_cvt_pk_bf16_f32 v148, v86, v87
	v_cvt_pk_bf16_f32 v149, v88, v89
	v_cvt_pk_bf16_f32 v150, v90, v91
	v_cvt_pk_bf16_f32 v151, v92, v93
	v_cvt_pk_bf16_f32 v152, v94, v95
	v_cvt_pk_bf16_f32 v153, v96, v97
	s_nop 0
	v_mfma_f32_32x32x16_bf16 v[50:65], v[154:157], v[146:149], v[50:65]
	v_add_f32_e32 v154, v98, v100
	v_add_f32_e32 v155, v99, v101
	v_add_f32_e32 v156, v102, v104
	v_add_f32_e32 v157, v103, v105
	v_add_f32_e32 v162, v106, v108
	v_add_f32_e32 v163, v107, v109
	v_pk_add_f32 v[164:165], v[110:111], v[112:113]
	v_mfma_f32_32x32x16_bf16 v[18:33], v[200:203], v[146:149], v[18:33]
	v_add_f32_e32 v146, v82, v84
	v_add_f32_e32 v147, v83, v85
	v_add_f32_e32 v148, v86, v88
	v_add_f32_e32 v149, v87, v89
	v_add_f32_e32 v166, v90, v92
	v_add_f32_e32 v167, v91, v93
	v_pk_add_f32 v[168:169], v[94:95], v[96:97]
	v_mfma_f32_32x32x16_bf16 v[50:65], v[158:161], v[150:153], v[50:65]
	v_add_f32_e32 v154, v154, v156
	v_add_f32_e32 v155, v155, v157
	v_add_f32_e32 v156, v162, v164
	v_add_f32_e32 v157, v163, v165
	v_add_f32_e32 v146, v146, v148
	v_add_f32_e32 v147, v147, v149
	v_pk_add_f32 v[148:149], v[166:167], v[168:169]
	v_mfma_f32_32x32x16_bf16 v[18:33], v[204:207], v[150:153], v[18:33]
	v_add_f32_e32 v150, v154, v156
	v_add_f32_e32 v151, v155, v157
	v_add_f32_e32 v146, v146, v148
	v_add_f32_e32 v147, v147, v149
	v_add_f32_e32 v146, v146, v150
	v_add_f32_e32 v147, v147, v151
	v_add_f32_e32 v146, v146, v147
	v_add_f32_e32 v175, v175, v146

.LBB0_345:
	ds_read_b64_tr_b16 v[146:147], v199 offset:0
	ds_read_b64_tr_b16 v[148:149], v199 offset:0x200
	ds_read_b64_tr_b16 v[150:151], v199 offset:0x400
	ds_read_b64_tr_b16 v[152:153], v199 offset:0x600
	ds_read_b64_tr_b16 v[154:155], v199 offset:0x800
	ds_read_b64_tr_b16 v[156:157], v199 offset:0xa00
	ds_read_b64_tr_b16 v[158:159], v199 offset:0xc00
	ds_read_b64_tr_b16 v[160:161], v199 offset:0xe00
	ds_read_b64_tr_b16 v[162:163], v199 offset:0x1000
	ds_read_b64_tr_b16 v[164:165], v199 offset:0x1200
	ds_read_b64_tr_b16 v[166:167], v199 offset:0x1400
	ds_read_b64_tr_b16 v[168:169], v199 offset:0x1600
	ds_read_b64_tr_b16 v[200:201], v199 offset:0x1800
	ds_read_b64_tr_b16 v[202:203], v199 offset:0x1a00
	ds_read_b64_tr_b16 v[204:205], v199 offset:0x1c00
	ds_read_b64_tr_b16 v[206:207], v199 offset:0x1e00
	v_exp_f32_e32 v208, v130
	v_exp_f32_e32 v209, v131
	v_exp_f32_e32 v210, v132
	v_exp_f32_e32 v211, v133
	v_exp_f32_e32 v212, v134
	v_exp_f32_e32 v213, v135
	v_exp_f32_e32 v214, v136
	v_exp_f32_e32 v215, v137
	v_exp_f32_e32 v138, v138
	v_exp_f32_e32 v139, v139
	v_exp_f32_e32 v140, v140
	v_exp_f32_e32 v141, v141
	v_exp_f32_e32 v142, v142
	v_exp_f32_e32 v143, v143
	v_exp_f32_e32 v144, v144
	v_exp_f32_e32 v145, v145
	v_cvt_pk_bf16_f32 v130, v208, v209
	v_cvt_pk_bf16_f32 v131, v210, v211
	v_cvt_pk_bf16_f32 v132, v212, v213
	v_cvt_pk_bf16_f32 v133, v214, v215
	v_cvt_pk_bf16_f32 v134, v138, v139
	v_cvt_pk_bf16_f32 v135, v140, v141
	v_cvt_pk_bf16_f32 v136, v142, v143
	v_cvt_pk_bf16_f32 v137, v144, v145
	s_waitcnt lgkmcnt(0)
	s_nop 0
	v_mfma_f32_32x32x16_bf16 v[66:81], v[146:149], v[130:133], v[66:81]
	v_exp_f32_e32 v146, v114
	v_exp_f32_e32 v147, v115
	v_exp_f32_e32 v148, v116
	v_exp_f32_e32 v149, v117
	v_mfma_f32_32x32x16_bf16 v[34:49], v[162:165], v[130:133], v[34:49]
	v_exp_f32_e32 v130, v118
	v_exp_f32_e32 v131, v119
	v_exp_f32_e32 v132, v120
	v_exp_f32_e32 v133, v121
	v_mfma_f32_32x32x16_bf16 v[66:81], v[150:153], v[134:137], v[66:81]
	v_exp_f32_e32 v122, v122
	v_exp_f32_e32 v123, v123
	v_exp_f32_e32 v124, v124
	v_exp_f32_e32 v125, v125
	v_mfma_f32_32x32x16_bf16 v[34:49], v[166:169], v[134:137], v[34:49]
	v_exp_f32_e32 v126, v126
	v_exp_f32_e32 v127, v127
	v_exp_f32_e32 v128, v128
	v_exp_f32_e32 v129, v129
	v_cvt_pk_bf16_f32 v114, v146, v147
	v_cvt_pk_bf16_f32 v115, v148, v149
	v_cvt_pk_bf16_f32 v116, v130, v131
	v_cvt_pk_bf16_f32 v117, v132, v133
	v_cvt_pk_bf16_f32 v118, v122, v123
	v_cvt_pk_bf16_f32 v119, v124, v125
	v_cvt_pk_bf16_f32 v120, v126, v127
	v_cvt_pk_bf16_f32 v121, v128, v129
	s_nop 0
	v_mfma_f32_32x32x16_bf16 v[66:81], v[154:157], v[114:117], v[66:81]
	v_add_f32_e32 v134, v208, v210
	v_add_f32_e32 v135, v209, v211
	v_add_f32_e32 v136, v212, v214
	v_add_f32_e32 v137, v213, v215
	v_add_f32_e32 v138, v138, v140
	v_add_f32_e32 v139, v139, v141
	v_pk_add_f32 v[140:141], v[142:143], v[144:145]
	v_mfma_f32_32x32x16_bf16 v[34:49], v[200:203], v[114:117], v[34:49]
	v_add_f32_e32 v114, v146, v148
	v_add_f32_e32 v115, v147, v149
	v_add_f32_e32 v116, v130, v132
	v_add_f32_e32 v117, v131, v133
	v_add_f32_e32 v122, v122, v124
	v_add_f32_e32 v123, v123, v125
	v_pk_add_f32 v[124:125], v[126:127], v[128:129]
	v_mfma_f32_32x32x16_bf16 v[66:81], v[158:161], v[118:121], v[66:81]
	v_add_f32_e32 v126, v134, v136
	v_add_f32_e32 v127, v135, v137
	v_add_f32_e32 v128, v138, v140
	v_add_f32_e32 v129, v139, v141
	v_add_f32_e32 v114, v114, v116
	v_add_f32_e32 v115, v115, v117
	v_pk_add_f32 v[116:117], v[122:123], v[124:125]
	v_mfma_f32_32x32x16_bf16 v[34:49], v[204:207], v[118:121], v[34:49]
	v_add_f32_e32 v118, v126, v128
	v_add_f32_e32 v119, v127, v129
	v_add_f32_e32 v114, v114, v116
	v_add_f32_e32 v115, v115, v117
	v_add_f32_e32 v114, v114, v118
	v_add_f32_e32 v115, v115, v119
	v_add_f32_e32 v114, v114, v115
	v_add_f32_e32 v174, v174, v114
	s_add_i32 s89, s89, -1
	s_cmp_eq_u32 s86, s12
	s_cbranch_scc1 .LBB0_349

.LBB0_537:
	s_and_b64 vcc, exec, s[76:77]
	v_add_u32_e32 v198, s84, v194
	s_cbranch_vccz .LBB0_539
	ds_read_b64_tr_b16 v[146:147], v198 offset:0
	ds_read_b64_tr_b16 v[148:149], v198 offset:0x200
	ds_read_b64_tr_b16 v[150:151], v198 offset:0x400
	ds_read_b64_tr_b16 v[152:153], v198 offset:0x600
	ds_read_b64_tr_b16 v[154:155], v198 offset:0x800
	ds_read_b64_tr_b16 v[156:157], v198 offset:0xa00
	ds_read_b64_tr_b16 v[158:159], v198 offset:0xc00
	ds_read_b64_tr_b16 v[160:161], v198 offset:0xe00
	ds_read_b64_tr_b16 v[162:163], v198 offset:0x1000
	ds_read_b64_tr_b16 v[164:165], v198 offset:0x1200
	ds_read_b64_tr_b16 v[166:167], v198 offset:0x1400
	ds_read_b64_tr_b16 v[168:169], v198 offset:0x1600
	ds_read_b64_tr_b16 v[200:201], v198 offset:0x1800
	ds_read_b64_tr_b16 v[202:203], v198 offset:0x1a00
	ds_read_b64_tr_b16 v[204:205], v198 offset:0x1c00
	ds_read_b64_tr_b16 v[206:207], v198 offset:0x1e00
	v_exp_f32_e32 v98, v98
	v_exp_f32_e32 v99, v99
	v_exp_f32_e32 v100, v100
	v_exp_f32_e32 v101, v101
	v_exp_f32_e32 v102, v102
	v_exp_f32_e32 v103, v103
	v_exp_f32_e32 v104, v104
	v_exp_f32_e32 v105, v105
	v_exp_f32_e32 v106, v106
	v_exp_f32_e32 v107, v107
	v_exp_f32_e32 v108, v108
	v_exp_f32_e32 v109, v109
	v_exp_f32_e32 v110, v110
	v_exp_f32_e32 v111, v111
	v_exp_f32_e32 v112, v112
	v_exp_f32_e32 v113, v113
	v_cvt_pk_bf16_f32 v208, v98, v99
	v_cvt_pk_bf16_f32 v209, v100, v101
	v_cvt_pk_bf16_f32 v210, v102, v103
	v_cvt_pk_bf16_f32 v211, v104, v105
	v_cvt_pk_bf16_f32 v212, v106, v107
	v_cvt_pk_bf16_f32 v213, v108, v109
	v_cvt_pk_bf16_f32 v214, v110, v111
	v_cvt_pk_bf16_f32 v215, v112, v113
	s_waitcnt lgkmcnt(0)
	s_nop 0
	v_mfma_f32_32x32x16_bf16 v[50:65], v[146:149], v[208:211], v[50:65]
	v_exp_f32_e32 v82, v82
	v_exp_f32_e32 v83, v83
	v_exp_f32_e32 v84, v84
	v_exp_f32_e32 v85, v85
	v_mfma_f32_32x32x16_bf16 v[18:33], v[162:165], v[208:211], v[18:33]
	v_exp_f32_e32 v86, v86
	v_exp_f32_e32 v87, v87
	v_exp_f32_e32 v88, v88
	v_exp_f32_e32 v89, v89
	v_mfma_f32_32x32x16_bf16 v[50:65], v[150:153], v[212:215], v[50:65]
	v_exp_f32_e32 v90, v90
	v_exp_f32_e32 v91, v91
	v_exp_f32_e32 v92, v92
	v_exp_f32_e32 v93, v93
	v_mfma_f32_32x32x16_bf16 v[18:33], v[166:169], v[212:215], v[18:33]
	v_exp_f32_e32 v94, v94
	v_exp_f32_e32 v95, v95
	v_exp_f32_e32 v96, v96
	v_exp_f32_e32 v97, v97
	v_cvt_pk_bf16_f32 v146, v82, v83
	v_cvt_pk_bf16_f32 v147, v84, v85
	v_cvt_pk_bf16_f32 v148, v86, v87
	v_cvt_pk_bf16_f32 v149, v88, v89
	v_cvt_pk_bf16_f32 v150, v90, v91
	v_cvt_pk_bf16_f32 v151, v92, v93
	v_cvt_pk_bf16_f32 v152, v94, v95
	v_cvt_pk_bf16_f32 v153, v96, v97
	s_nop 0
	v_mfma_f32_32x32x16_bf16 v[50:65], v[154:157], v[146:149], v[50:65]
	v_add_f32_e32 v154, v98, v100
	v_add_f32_e32 v155, v99, v101
	v_add_f32_e32 v156, v102, v104
	v_add_f32_e32 v157, v103, v105
	v_add_f32_e32 v162, v106, v108
	v_add_f32_e32 v163, v107, v109
	v_pk_add_f32 v[164:165], v[110:111], v[112:113]
	v_mfma_f32_32x32x16_bf16 v[18:33], v[200:203], v[146:149], v[18:33]
	v_add_f32_e32 v146, v82, v84
	v_add_f32_e32 v147, v83, v85
	v_add_f32_e32 v148, v86, v88
	v_add_f32_e32 v149, v87, v89
	v_add_f32_e32 v166, v90, v92
	v_add_f32_e32 v167, v91, v93
	v_pk_add_f32 v[168:169], v[94:95], v[96:97]
	v_mfma_f32_32x32x16_bf16 v[50:65], v[158:161], v[150:153], v[50:65]
	v_add_f32_e32 v154, v154, v156
	v_add_f32_e32 v155, v155, v157
	v_add_f32_e32 v156, v162, v164
	v_add_f32_e32 v157, v163, v165
	v_add_f32_e32 v146, v146, v148
	v_add_f32_e32 v147, v147, v149
	v_pk_add_f32 v[148:149], v[166:167], v[168:169]
	v_mfma_f32_32x32x16_bf16 v[18:33], v[204:207], v[150:153], v[18:33]
	v_add_f32_e32 v150, v154, v156
	v_add_f32_e32 v151, v155, v157
	v_add_f32_e32 v146, v146, v148
	v_add_f32_e32 v147, v147, v149
	v_add_f32_e32 v146, v146, v150
	v_add_f32_e32 v147, v147, v151
	v_add_f32_e32 v146, v146, v147
	v_add_f32_e32 v175, v175, v146

.LBB0_563:
	ds_read_b64_tr_b16 v[146:147], v198 offset:0
	ds_read_b64_tr_b16 v[148:149], v198 offset:0x200
	ds_read_b64_tr_b16 v[150:151], v198 offset:0x400
	ds_read_b64_tr_b16 v[152:153], v198 offset:0x600
	ds_read_b64_tr_b16 v[154:155], v198 offset:0x800
	ds_read_b64_tr_b16 v[156:157], v198 offset:0xa00
	ds_read_b64_tr_b16 v[158:159], v198 offset:0xc00
	ds_read_b64_tr_b16 v[160:161], v198 offset:0xe00
	ds_read_b64_tr_b16 v[162:163], v198 offset:0x1000
	ds_read_b64_tr_b16 v[164:165], v198 offset:0x1200
	ds_read_b64_tr_b16 v[166:167], v198 offset:0x1400
	ds_read_b64_tr_b16 v[168:169], v198 offset:0x1600
	ds_read_b64_tr_b16 v[200:201], v198 offset:0x1800
	ds_read_b64_tr_b16 v[202:203], v198 offset:0x1a00
	ds_read_b64_tr_b16 v[204:205], v198 offset:0x1c00
	ds_read_b64_tr_b16 v[206:207], v198 offset:0x1e00
	v_exp_f32_e32 v198, v130
	v_exp_f32_e32 v199, v131
	v_exp_f32_e32 v208, v132
	v_exp_f32_e32 v209, v133
	v_exp_f32_e32 v210, v134
	v_exp_f32_e32 v211, v135
	v_exp_f32_e32 v212, v136
	v_exp_f32_e32 v213, v137
	v_exp_f32_e32 v138, v138
	v_exp_f32_e32 v139, v139
	v_exp_f32_e32 v140, v140
	v_exp_f32_e32 v141, v141
	v_exp_f32_e32 v142, v142
	v_exp_f32_e32 v143, v143
	v_exp_f32_e32 v144, v144
	v_exp_f32_e32 v145, v145
	v_cvt_pk_bf16_f32 v130, v198, v199
	v_cvt_pk_bf16_f32 v131, v208, v209
	v_cvt_pk_bf16_f32 v132, v210, v211
	v_cvt_pk_bf16_f32 v133, v212, v213
	v_cvt_pk_bf16_f32 v134, v138, v139
	v_cvt_pk_bf16_f32 v135, v140, v141
	v_cvt_pk_bf16_f32 v136, v142, v143
	v_cvt_pk_bf16_f32 v137, v144, v145
	s_waitcnt lgkmcnt(0)
	s_nop 0
	v_mfma_f32_32x32x16_bf16 v[66:81], v[146:149], v[130:133], v[66:81]
	v_exp_f32_e32 v146, v114
	v_exp_f32_e32 v147, v115
	v_exp_f32_e32 v148, v116
	v_exp_f32_e32 v149, v117
	v_mfma_f32_32x32x16_bf16 v[34:49], v[162:165], v[130:133], v[34:49]
	v_exp_f32_e32 v130, v118
	v_exp_f32_e32 v131, v119
	v_exp_f32_e32 v132, v120
	v_exp_f32_e32 v133, v121
	v_mfma_f32_32x32x16_bf16 v[66:81], v[150:153], v[134:137], v[66:81]
	v_exp_f32_e32 v122, v122
	v_exp_f32_e32 v123, v123
	v_exp_f32_e32 v124, v124
	v_exp_f32_e32 v125, v125
	v_mfma_f32_32x32x16_bf16 v[34:49], v[166:169], v[134:137], v[34:49]
	v_exp_f32_e32 v126, v126
	v_exp_f32_e32 v127, v127
	v_exp_f32_e32 v128, v128
	v_exp_f32_e32 v129, v129
	v_cvt_pk_bf16_f32 v114, v146, v147
	v_cvt_pk_bf16_f32 v115, v148, v149
	v_cvt_pk_bf16_f32 v116, v130, v131
	v_cvt_pk_bf16_f32 v117, v132, v133
	v_cvt_pk_bf16_f32 v118, v122, v123
	v_cvt_pk_bf16_f32 v119, v124, v125
	v_cvt_pk_bf16_f32 v120, v126, v127
	v_cvt_pk_bf16_f32 v121, v128, v129
	s_nop 0
	v_mfma_f32_32x32x16_bf16 v[66:81], v[154:157], v[114:117], v[66:81]
	v_add_f32_e32 v134, v198, v208
	v_add_f32_e32 v135, v199, v209
	v_add_f32_e32 v136, v210, v212
	v_add_f32_e32 v137, v211, v213
	v_add_f32_e32 v138, v138, v140
	v_add_f32_e32 v139, v139, v141
	v_pk_add_f32 v[140:141], v[142:143], v[144:145]
	v_mfma_f32_32x32x16_bf16 v[34:49], v[200:203], v[114:117], v[34:49]
	v_add_f32_e32 v114, v146, v148
	v_add_f32_e32 v115, v147, v149
	v_add_f32_e32 v116, v130, v132
	v_add_f32_e32 v117, v131, v133
	v_add_f32_e32 v122, v122, v124
	v_add_f32_e32 v123, v123, v125
	v_pk_add_f32 v[124:125], v[126:127], v[128:129]
	v_mfma_f32_32x32x16_bf16 v[66:81], v[158:161], v[118:121], v[66:81]
	v_add_f32_e32 v126, v134, v136
	v_add_f32_e32 v127, v135, v137
	v_add_f32_e32 v128, v138, v140
	v_add_f32_e32 v129, v139, v141
	v_add_f32_e32 v114, v114, v116
	v_add_f32_e32 v115, v115, v117
	v_pk_add_f32 v[116:117], v[122:123], v[124:125]
	v_mfma_f32_32x32x16_bf16 v[34:49], v[204:207], v[118:121], v[34:49]
	v_add_f32_e32 v118, v126, v128
	v_add_f32_e32 v119, v127, v129
	v_add_f32_e32 v114, v114, v116
	v_add_f32_e32 v115, v115, v117
	v_add_f32_e32 v114, v114, v118
	v_add_f32_e32 v115, v115, v119
	v_add_f32_e32 v114, v114, v115
	v_add_f32_e32 v174, v174, v114
	s_add_i32 s85, s85, -1
	s_cmp_eq_u32 s82, s12
	s_cbranch_scc1 .LBB0_569
